# v13: v11 + first counted wait of each GEMM unit's peeled K-iteration relaxed by the epilogue's store count (vmcnt(8)->vmcnt(8+S)): store acks of the previous unit overlap the first load segment
# speedup vs baseline: 1.0001x; 1.0001x over previous
.LBB0_228:
	s_ashr_i32 s21, s20, 31
	s_lshl_b64 s[22:23], s[20:21], 21
	s_add_u32 s22, s35, s22
	s_addc_u32 s23, s38, s23
	s_and_b64 s[24:25], s[4:5], exec
	s_cselect_b32 s21, s23, s29
	s_cselect_b32 s59, s22, s28
	s_ashr_i32 s19, s18, 31
	s_lshl_b64 s[24:25], s[18:19], 21
	s_add_u32 s24, s39, s24
	s_addc_u32 s25, s45, s25
	s_and_b64 s[36:37], s[4:5], exec
	s_cselect_b32 s19, s25, s31
	s_cselect_b32 s60, s24, s30
	s_add_u32 s28, s28, 0x100080
	s_addc_u32 s29, s29, 0
	s_add_u32 s61, s30, 0x100
	s_addc_u32 s62, s31, 0
	s_mov_b32 s67, -2
	ds_read_b128 v[144:147], v149
	ds_read_b128 v[154:157], v149 offset:1024
	ds_read_b128 v[158:161], v149 offset:2048
	ds_read_b128 v[162:165], v149 offset:3072
	ds_read_b128 v[166:169], v150
	ds_read_b128 v[170:173], v150 offset:1024
	ds_read_b128 v[174:177], v150 offset:2048
	ds_read_b128 v[178:181], v150 offset:3072
	s_add_u32 s30, s28, 0xfff00080
	s_addc_u32 s31, s29, -1
	s_cmp_eq_u32 s67, 60
	s_cselect_b32 s37, s21, s31
	s_cselect_b32 s36, s59, s30
	s_cselect_b32 s31, s19, s62
	s_cselect_b32 s30, s60, s61
	v_lshl_add_u64 v[214:215], s[28:29], 0, v[136:137]
	s_add_i32 m0, s27, 0xc000
	ds_read_b128 v[182:185], v151
	ds_read_b128 v[186:189], v151 offset:1024
	ds_read_b128 v[190:193], v151 offset:2048
	ds_read_b128 v[194:197], v151 offset:3072
	ds_read_b128 v[198:201], v151 offset:4096
	ds_read_b128 v[202:205], v151 offset:5120
	ds_read_b128 v[206:209], v151 offset:6144
	ds_read_b128 v[210:213], v151 offset:7168
	global_load_lds_dwordx4 v[214:215], off
	v_lshl_add_u64 v[214:215], s[28:29], 0, v[138:139]
	s_add_i32 m0, s27, 0xe000
	s_nop 0
	global_load_lds_dwordx4 v[214:215], off
	s_waitcnt vmcnt(24)
	s_waitcnt lgkmcnt(0)
	s_barrier
	s_setprio 1
	s_waitcnt lgkmcnt(0)
	v_mfma_f32_16x16x32_bf16 v[124:127], v[144:147], v[182:185], 0
	v_mfma_f32_16x16x32_bf16 v[120:123], v[158:161], v[182:185], 0
	v_mfma_f32_16x16x32_bf16 v[112:115], v[144:147], v[190:193], 0
	v_mfma_f32_16x16x32_bf16 v[104:107], v[158:161], v[190:193], 0
	v_mfma_f32_16x16x32_bf16 v[96:99], v[144:147], v[198:201], 0
	v_mfma_f32_16x16x32_bf16 v[88:91], v[158:161], v[198:201], 0
	v_mfma_f32_16x16x32_bf16 v[80:83], v[144:147], v[206:209], 0
	v_mfma_f32_16x16x32_bf16 v[72:75], v[158:161], v[206:209], 0
	v_mfma_f32_16x16x32_bf16 v[124:127], v[154:157], v[186:189], v[124:127]
	v_mfma_f32_16x16x32_bf16 v[120:123], v[162:165], v[186:189], v[120:123]
	v_mfma_f32_16x16x32_bf16 v[112:115], v[154:157], v[194:197], v[112:115]
	v_mfma_f32_16x16x32_bf16 v[104:107], v[162:165], v[194:197], v[104:107]
	v_mfma_f32_16x16x32_bf16 v[96:99], v[154:157], v[202:205], v[96:99]
	v_mfma_f32_16x16x32_bf16 v[88:91], v[162:165], v[202:205], v[88:91]
	v_mfma_f32_16x16x32_bf16 v[80:83], v[154:157], v[210:213], v[80:83]
	v_mfma_f32_16x16x32_bf16 v[72:75], v[162:165], v[210:213], v[72:75]
	s_setprio 0
	s_setprio 1
	v_mfma_f32_16x16x32_bf16 v[116:119], v[166:169], v[182:185], 0
	v_mfma_f32_16x16x32_bf16 v[108:111], v[174:177], v[182:185], 0
	v_mfma_f32_16x16x32_bf16 v[100:103], v[166:169], v[190:193], 0
	v_mfma_f32_16x16x32_bf16 v[92:95], v[174:177], v[190:193], 0
	v_mfma_f32_16x16x32_bf16 v[84:87], v[166:169], v[198:201], 0
	v_mfma_f32_16x16x32_bf16 v[76:79], v[174:177], v[198:201], 0
	v_mfma_f32_16x16x32_bf16 v[68:71], v[166:169], v[206:209], 0
	v_mfma_f32_16x16x32_bf16 v[64:67], v[174:177], v[206:209], 0
	v_mfma_f32_16x16x32_bf16 v[116:119], v[170:173], v[186:189], v[116:119]
	v_mfma_f32_16x16x32_bf16 v[108:111], v[178:181], v[186:189], v[108:111]
	v_mfma_f32_16x16x32_bf16 v[100:103], v[170:173], v[194:197], v[100:103]
	v_mfma_f32_16x16x32_bf16 v[92:95], v[178:181], v[194:197], v[92:95]
	v_mfma_f32_16x16x32_bf16 v[84:87], v[170:173], v[202:205], v[84:87]
	v_mfma_f32_16x16x32_bf16 v[76:79], v[178:181], v[202:205], v[76:79]
	v_mfma_f32_16x16x32_bf16 v[68:71], v[170:173], v[210:213], v[68:71]
	v_mfma_f32_16x16x32_bf16 v[64:67], v[178:181], v[210:213], v[64:67]
	s_setprio 0
	s_barrier
	s_add_i32 s68, s56, s46
	v_lshl_add_u64 v[214:215], s[30:31], 0, v[130:131]
	s_mov_b32 m0, s68
	ds_read_b128 v[182:185], v151 offset:16384
	ds_read_b128 v[186:189], v151 offset:17408
	ds_read_b128 v[190:193], v151 offset:18432
	ds_read_b128 v[194:197], v151 offset:19456
	ds_read_b128 v[198:201], v151 offset:20480
	ds_read_b128 v[202:205], v151 offset:21504
	ds_read_b128 v[206:209], v151 offset:22528
	ds_read_b128 v[210:213], v151 offset:23552
	global_load_lds_dwordx4 v[214:215], off
	s_add_i32 m0, s68, 0x2000
	s_add_u32 s68, s30, 0x100000
	v_lshl_add_u64 v[216:217], s[30:31], 0, v[134:135]
	s_addc_u32 s69, s31, 0
	s_add_i32 s70, s57, s46
	global_load_lds_dwordx4 v[216:217], off
	v_lshl_add_u64 v[218:219], s[68:69], 0, v[130:131]
	s_mov_b32 m0, s70
	v_lshl_add_u64 v[220:221], s[36:37], 0, v[132:133]
	global_load_lds_dwordx4 v[218:219], off
	v_lshl_add_u64 v[218:219], s[68:69], 0, v[134:135]
	s_add_i32 m0, s70, 0x2000
	s_nop 0
	global_load_lds_dwordx4 v[218:219], off
	v_lshl_add_u64 v[218:219], s[36:37], 0, v[128:129]
	s_mov_b32 m0, s27
	s_nop 0
	global_load_lds_dwordx4 v[218:219], off
	s_mov_b32 m0, s47
	s_nop 0
	global_load_lds_dwordx4 v[220:221], off
	s_waitcnt vmcnt(8)
	s_waitcnt lgkmcnt(0)
	s_barrier
	s_setprio 1
	s_waitcnt lgkmcnt(0)
	v_mfma_f32_16x16x32_bf16 v[60:63], v[144:147], v[182:185], 0
	v_mfma_f32_16x16x32_bf16 v[56:59], v[158:161], v[182:185], 0
	v_mfma_f32_16x16x32_bf16 v[48:51], v[144:147], v[190:193], 0
	v_mfma_f32_16x16x32_bf16 v[40:43], v[158:161], v[190:193], 0
	v_mfma_f32_16x16x32_bf16 v[32:35], v[144:147], v[198:201], 0
	v_mfma_f32_16x16x32_bf16 v[24:27], v[158:161], v[198:201], 0
	v_mfma_f32_16x16x32_bf16 v[16:19], v[144:147], v[206:209], 0
	v_mfma_f32_16x16x32_bf16 v[8:11], v[158:161], v[206:209], 0
	v_mfma_f32_16x16x32_bf16 v[60:63], v[154:157], v[186:189], v[60:63]
	v_mfma_f32_16x16x32_bf16 v[56:59], v[162:165], v[186:189], v[56:59]
	v_mfma_f32_16x16x32_bf16 v[48:51], v[154:157], v[194:197], v[48:51]
	v_mfma_f32_16x16x32_bf16 v[40:43], v[162:165], v[194:197], v[40:43]
	v_mfma_f32_16x16x32_bf16 v[32:35], v[154:157], v[202:205], v[32:35]
	v_mfma_f32_16x16x32_bf16 v[24:27], v[162:165], v[202:205], v[24:27]
	v_mfma_f32_16x16x32_bf16 v[16:19], v[154:157], v[210:213], v[16:19]
	v_mfma_f32_16x16x32_bf16 v[8:11], v[162:165], v[210:213], v[8:11]
	s_setprio 0
	s_setprio 1
	v_mfma_f32_16x16x32_bf16 v[52:55], v[166:169], v[182:185], 0
	v_mfma_f32_16x16x32_bf16 v[44:47], v[174:177], v[182:185], 0
	v_mfma_f32_16x16x32_bf16 v[36:39], v[166:169], v[190:193], 0
	v_mfma_f32_16x16x32_bf16 v[28:31], v[174:177], v[190:193], 0
	v_mfma_f32_16x16x32_bf16 v[20:23], v[166:169], v[198:201], 0
	v_mfma_f32_16x16x32_bf16 v[12:15], v[174:177], v[198:201], 0
	v_mfma_f32_16x16x32_bf16 v[4:7], v[166:169], v[206:209], 0
	v_mfma_f32_16x16x32_bf16 v[0:3], v[174:177], v[206:209], 0
	v_mfma_f32_16x16x32_bf16 v[52:55], v[170:173], v[186:189], v[52:55]
	v_mfma_f32_16x16x32_bf16 v[44:47], v[178:181], v[186:189], v[44:47]
	v_mfma_f32_16x16x32_bf16 v[36:39], v[170:173], v[194:197], v[36:39]
	v_mfma_f32_16x16x32_bf16 v[28:31], v[178:181], v[194:197], v[28:31]
	v_mfma_f32_16x16x32_bf16 v[20:23], v[170:173], v[202:205], v[20:23]
	v_mfma_f32_16x16x32_bf16 v[12:15], v[178:181], v[202:205], v[12:15]
	v_mfma_f32_16x16x32_bf16 v[4:7], v[170:173], v[210:213], v[4:7]
	v_mfma_f32_16x16x32_bf16 v[0:3], v[178:181], v[210:213], v[0:3]
	s_setprio 0
	s_barrier
	s_add_i32 s68, 0, 0x18000
	v_add_u32_e32 v153, s68, v148
	s_add_i32 s69, 0, 0x1c000
	ds_read_b128 v[144:147], v153
	ds_read_b128 v[154:157], v153 offset:1024
	ds_read_b128 v[158:161], v153 offset:2048
	ds_read_b128 v[162:165], v153 offset:3072
	v_add_u32_e32 v153, s69, v148
	ds_read_b128 v[166:169], v153
	ds_read_b128 v[170:173], v153 offset:1024
	ds_read_b128 v[174:177], v153 offset:2048
	ds_read_b128 v[178:181], v153 offset:3072
	s_add_u32 s36, s36, 0x100000
	s_addc_u32 s37, s37, 0
	s_mov_b32 m0, s48
	v_lshl_add_u64 v[222:223], s[36:37], 0, v[128:129]
	ds_read_b128 v[182:185], v151 offset:32768
	ds_read_b128 v[186:189], v151 offset:33792
	ds_read_b128 v[190:193], v151 offset:34816
	ds_read_b128 v[194:197], v151 offset:35840
	ds_read_b128 v[198:201], v151 offset:36864
	ds_read_b128 v[202:205], v151 offset:37888
	ds_read_b128 v[206:209], v151 offset:38912
	ds_read_b128 v[210:213], v151 offset:39936
	global_load_lds_dwordx4 v[222:223], off
	v_lshl_add_u64 v[222:223], s[36:37], 0, v[132:133]
	s_mov_b32 m0, s49
	s_nop 0
	global_load_lds_dwordx4 v[222:223], off
	s_waitcnt vmcnt(8)
	s_waitcnt lgkmcnt(0)
	s_barrier
	s_setprio 1
	s_waitcnt lgkmcnt(0)
	v_mfma_f32_16x16x32_bf16 v[124:127], v[144:147], v[182:185], v[124:127]
	v_mfma_f32_16x16x32_bf16 v[120:123], v[158:161], v[182:185], v[120:123]
	v_mfma_f32_16x16x32_bf16 v[112:115], v[144:147], v[190:193], v[112:115]
	v_mfma_f32_16x16x32_bf16 v[104:107], v[158:161], v[190:193], v[104:107]
	v_mfma_f32_16x16x32_bf16 v[96:99], v[144:147], v[198:201], v[96:99]
	v_mfma_f32_16x16x32_bf16 v[88:91], v[158:161], v[198:201], v[88:91]
	v_mfma_f32_16x16x32_bf16 v[80:83], v[144:147], v[206:209], v[80:83]
	v_mfma_f32_16x16x32_bf16 v[72:75], v[158:161], v[206:209], v[72:75]
	v_mfma_f32_16x16x32_bf16 v[124:127], v[154:157], v[186:189], v[124:127]
	v_mfma_f32_16x16x32_bf16 v[120:123], v[162:165], v[186:189], v[120:123]
	v_mfma_f32_16x16x32_bf16 v[112:115], v[154:157], v[194:197], v[112:115]
	v_mfma_f32_16x16x32_bf16 v[104:107], v[162:165], v[194:197], v[104:107]
	v_mfma_f32_16x16x32_bf16 v[96:99], v[154:157], v[202:205], v[96:99]
	v_mfma_f32_16x16x32_bf16 v[88:91], v[162:165], v[202:205], v[88:91]
	v_mfma_f32_16x16x32_bf16 v[80:83], v[154:157], v[210:213], v[80:83]
	v_mfma_f32_16x16x32_bf16 v[72:75], v[162:165], v[210:213], v[72:75]
	s_setprio 0
	s_setprio 1
	v_mfma_f32_16x16x32_bf16 v[116:119], v[166:169], v[182:185], v[116:119]
	v_mfma_f32_16x16x32_bf16 v[108:111], v[174:177], v[182:185], v[108:111]
	v_mfma_f32_16x16x32_bf16 v[100:103], v[166:169], v[190:193], v[100:103]
	v_mfma_f32_16x16x32_bf16 v[92:95], v[174:177], v[190:193], v[92:95]
	v_mfma_f32_16x16x32_bf16 v[84:87], v[166:169], v[198:201], v[84:87]
	v_mfma_f32_16x16x32_bf16 v[76:79], v[174:177], v[198:201], v[76:79]
	v_mfma_f32_16x16x32_bf16 v[68:71], v[166:169], v[206:209], v[68:71]
	v_mfma_f32_16x16x32_bf16 v[64:67], v[174:177], v[206:209], v[64:67]
	v_mfma_f32_16x16x32_bf16 v[116:119], v[170:173], v[186:189], v[116:119]
	v_mfma_f32_16x16x32_bf16 v[108:111], v[178:181], v[186:189], v[108:111]
	v_mfma_f32_16x16x32_bf16 v[100:103], v[170:173], v[194:197], v[100:103]
	v_mfma_f32_16x16x32_bf16 v[92:95], v[178:181], v[194:197], v[92:95]
	v_mfma_f32_16x16x32_bf16 v[84:87], v[170:173], v[202:205], v[84:87]
	v_mfma_f32_16x16x32_bf16 v[76:79], v[178:181], v[202:205], v[76:79]
	v_mfma_f32_16x16x32_bf16 v[68:71], v[170:173], v[210:213], v[68:71]
	v_mfma_f32_16x16x32_bf16 v[64:67], v[178:181], v[210:213], v[64:67]
	s_setprio 0
	s_barrier
	s_add_i32 s36, s68, s46
	v_lshl_add_u64 v[214:215], v[214:215], 0, s[14:15]
	s_mov_b32 m0, s36
	ds_read_b128 v[182:185], v151 offset:49152
	ds_read_b128 v[186:189], v151 offset:50176
	ds_read_b128 v[190:193], v151 offset:51200
	ds_read_b128 v[194:197], v151 offset:52224
	ds_read_b128 v[198:201], v151 offset:53248
	ds_read_b128 v[202:205], v151 offset:54272
	ds_read_b128 v[206:209], v151 offset:55296
	ds_read_b128 v[210:213], v151 offset:56320
	global_load_lds_dwordx4 v[214:215], off
	s_add_i32 m0, s36, 0x2000
	s_add_u32 s30, s30, 0x100080
	v_lshl_add_u64 v[214:215], v[216:217], 0, s[14:15]
	s_addc_u32 s31, s31, 0
	s_add_i32 s36, s69, s46
	global_load_lds_dwordx4 v[214:215], off
	v_lshl_add_u64 v[214:215], s[30:31], 0, v[130:131]
	s_mov_b32 m0, s36
	s_nop 0
	global_load_lds_dwordx4 v[214:215], off
	v_lshl_add_u64 v[214:215], s[30:31], 0, v[134:135]
	s_add_i32 m0, s36, 0x2000
	s_nop 0
	global_load_lds_dwordx4 v[214:215], off
	v_lshl_add_u64 v[214:215], v[218:219], 0, s[14:15]
	s_mov_b32 m0, s53
	s_nop 0
	global_load_lds_dwordx4 v[214:215], off
	v_lshl_add_u64 v[214:215], v[220:221], 0, s[14:15]
	s_mov_b32 m0, s54
	s_nop 0
	global_load_lds_dwordx4 v[214:215], off
	s_waitcnt vmcnt(8)
	s_waitcnt lgkmcnt(0)
	s_barrier
	s_setprio 1
	s_waitcnt lgkmcnt(0)
	v_mfma_f32_16x16x32_bf16 v[60:63], v[144:147], v[182:185], v[60:63]
	v_mfma_f32_16x16x32_bf16 v[56:59], v[158:161], v[182:185], v[56:59]
	v_mfma_f32_16x16x32_bf16 v[48:51], v[144:147], v[190:193], v[48:51]
	v_mfma_f32_16x16x32_bf16 v[40:43], v[158:161], v[190:193], v[40:43]
	v_mfma_f32_16x16x32_bf16 v[32:35], v[144:147], v[198:201], v[32:35]
	v_mfma_f32_16x16x32_bf16 v[24:27], v[158:161], v[198:201], v[24:27]
	v_mfma_f32_16x16x32_bf16 v[16:19], v[144:147], v[206:209], v[16:19]
	v_mfma_f32_16x16x32_bf16 v[8:11], v[158:161], v[206:209], v[8:11]
	v_mfma_f32_16x16x32_bf16 v[60:63], v[154:157], v[186:189], v[60:63]
	v_mfma_f32_16x16x32_bf16 v[56:59], v[162:165], v[186:189], v[56:59]
	v_mfma_f32_16x16x32_bf16 v[48:51], v[154:157], v[194:197], v[48:51]
	v_mfma_f32_16x16x32_bf16 v[40:43], v[162:165], v[194:197], v[40:43]
	v_mfma_f32_16x16x32_bf16 v[32:35], v[154:157], v[202:205], v[32:35]
	v_mfma_f32_16x16x32_bf16 v[24:27], v[162:165], v[202:205], v[24:27]
	v_mfma_f32_16x16x32_bf16 v[16:19], v[154:157], v[210:213], v[16:19]
	v_mfma_f32_16x16x32_bf16 v[8:11], v[162:165], v[210:213], v[8:11]
	s_setprio 0
	s_setprio 1
	v_mfma_f32_16x16x32_bf16 v[52:55], v[166:169], v[182:185], v[52:55]
	v_mfma_f32_16x16x32_bf16 v[44:47], v[174:177], v[182:185], v[44:47]
	v_mfma_f32_16x16x32_bf16 v[36:39], v[166:169], v[190:193], v[36:39]
	v_mfma_f32_16x16x32_bf16 v[28:31], v[174:177], v[190:193], v[28:31]
	v_mfma_f32_16x16x32_bf16 v[20:23], v[166:169], v[198:201], v[20:23]
	v_mfma_f32_16x16x32_bf16 v[12:15], v[174:177], v[198:201], v[12:15]
	v_mfma_f32_16x16x32_bf16 v[4:7], v[166:169], v[206:209], v[4:7]
	v_mfma_f32_16x16x32_bf16 v[0:3], v[174:177], v[206:209], v[0:3]
	v_mfma_f32_16x16x32_bf16 v[52:55], v[170:173], v[186:189], v[52:55]
	v_mfma_f32_16x16x32_bf16 v[44:47], v[178:181], v[186:189], v[44:47]
	v_mfma_f32_16x16x32_bf16 v[36:39], v[170:173], v[194:197], v[36:39]
	v_mfma_f32_16x16x32_bf16 v[28:31], v[178:181], v[194:197], v[28:31]
	v_mfma_f32_16x16x32_bf16 v[20:23], v[170:173], v[202:205], v[20:23]
	v_mfma_f32_16x16x32_bf16 v[12:15], v[178:181], v[202:205], v[12:15]
	v_mfma_f32_16x16x32_bf16 v[4:7], v[170:173], v[210:213], v[4:7]
	v_mfma_f32_16x16x32_bf16 v[0:3], v[178:181], v[210:213], v[0:3]
	s_setprio 0
	s_barrier
	s_add_i32 s67, s67, 2
	s_add_u32 s28, s28, 0x100
	s_addc_u32 s29, s29, 0
	s_add_u32 s61, s61, 0x100
	s_addc_u32 s62, s62, 0
	s_cmp_gt_u32 s67, 61
	s_cbranch_scc1 .Lpost_p1

.LBB0_632:
	s_ashr_i32 s29, s28, 31
	s_lshl_b64 s[30:31], s[28:29], 20
	s_add_u32 s30, s2, s30
	s_addc_u32 s31, s25, s31
	s_and_b64 s[36:37], s[4:5], exec
	s_cselect_b32 s29, s31, s39
	s_cselect_b32 s71, s30, s38
	s_ashr_i32 s27, s26, 31
	s_lshl_b64 s[36:37], s[26:27], 20
	s_add_u32 s36, s34, s36
	s_addc_u32 s37, s35, s37
	s_and_b64 s[50:51], s[4:5], exec
	s_cselect_b32 s72, s37, s49
	s_cselect_b32 s73, s36, s48
	s_lshl_b32 s27, s46, 8
	s_add_i32 s27, s27, s58
	s_add_u32 s74, s48, 0x100
	v_lshl_add_u64 v[144:145], s[38:39], 0, v[136:137]
	v_lshl_add_u64 v[146:147], s[38:39], 0, v[138:139]
	s_addc_u32 s75, s49, 0
	s_mov_b32 s76, -2
	s_mov_b64 s[46:47], 0
	v_add_u32_e32 v160, s68, v164
	v_add_u32_e32 v178, s69, v164
	s_add_u32 s48, s38, s46
	ds_read_b128 v[148:151], v160
	ds_read_b128 v[152:155], v160 offset:1024
	ds_read_b128 v[156:159], v160 offset:2048
	ds_read_b128 v[160:163], v160 offset:3072
	ds_read_b128 v[166:169], v178
	ds_read_b128 v[170:173], v178 offset:1024
	ds_read_b128 v[174:177], v178 offset:2048
	ds_read_b128 v[178:181], v178 offset:3072
	s_addc_u32 s49, s39, s47
	s_add_u32 s48, s48, 0x100
	s_addc_u32 s49, s49, 0
	s_add_u32 s67, s74, s46
	s_addc_u32 s77, s75, s47
	s_cmpk_eq_i32 s46, 0xf00
	s_cselect_b32 s51, s29, s49
	s_cselect_b32 s50, s71, s48
	s_cselect_b32 s49, s72, s77
	s_cselect_b32 s48, s73, s67
	v_lshl_add_u64 v[214:215], v[144:145], 0, s[46:47]
	s_add_i32 m0, s54, 0xc000
	ds_read_b128 v[182:185], v165
	ds_read_b128 v[186:189], v165 offset:1024
	ds_read_b128 v[190:193], v165 offset:2048
	ds_read_b128 v[194:197], v165 offset:3072
	ds_read_b128 v[198:201], v165 offset:4096
	ds_read_b128 v[202:205], v165 offset:5120
	ds_read_b128 v[206:209], v165 offset:6144
	ds_read_b128 v[210:213], v165 offset:7168
	global_load_lds_dwordx4 v[214:215], off
	v_lshl_add_u64 v[214:215], v[146:147], 0, s[46:47]
	s_add_i32 m0, s54, 0xe000
	s_nop 0
	global_load_lds_dwordx4 v[214:215], off
	s_waitcnt vmcnt(24)
	s_waitcnt lgkmcnt(0)
	s_barrier
	s_setprio 1
	s_waitcnt lgkmcnt(0)
	v_mfma_i32_16x16x64_i8 v[124:127], v[148:151], v[182:185], 0
	v_mfma_i32_16x16x64_i8 v[120:123], v[156:159], v[182:185], 0
	v_mfma_i32_16x16x64_i8 v[108:111], v[148:151], v[190:193], 0
	v_mfma_i32_16x16x64_i8 v[104:107], v[156:159], v[190:193], 0
	v_mfma_i32_16x16x64_i8 v[92:95], v[148:151], v[198:201], 0
	v_mfma_i32_16x16x64_i8 v[88:91], v[156:159], v[198:201], 0
	v_mfma_i32_16x16x64_i8 v[76:79], v[148:151], v[206:209], 0
	v_mfma_i32_16x16x64_i8 v[72:75], v[156:159], v[206:209], 0
	v_mfma_i32_16x16x64_i8 v[124:127], v[152:155], v[186:189], v[124:127]
	v_mfma_i32_16x16x64_i8 v[120:123], v[160:163], v[186:189], v[120:123]
	v_mfma_i32_16x16x64_i8 v[108:111], v[152:155], v[194:197], v[108:111]
	v_mfma_i32_16x16x64_i8 v[104:107], v[160:163], v[194:197], v[104:107]
	v_mfma_i32_16x16x64_i8 v[92:95], v[152:155], v[202:205], v[92:95]
	v_mfma_i32_16x16x64_i8 v[88:91], v[160:163], v[202:205], v[88:91]
	v_mfma_i32_16x16x64_i8 v[76:79], v[152:155], v[210:213], v[76:79]
	v_mfma_i32_16x16x64_i8 v[72:75], v[160:163], v[210:213], v[72:75]
	s_setprio 0
	s_setprio 1
	v_mfma_i32_16x16x64_i8 v[116:119], v[166:169], v[182:185], 0
	v_mfma_i32_16x16x64_i8 v[112:115], v[174:177], v[182:185], 0
	v_mfma_i32_16x16x64_i8 v[100:103], v[166:169], v[190:193], 0
	v_mfma_i32_16x16x64_i8 v[96:99], v[174:177], v[190:193], 0
	v_mfma_i32_16x16x64_i8 v[84:87], v[166:169], v[198:201], 0
	v_mfma_i32_16x16x64_i8 v[80:83], v[174:177], v[198:201], 0
	v_mfma_i32_16x16x64_i8 v[68:71], v[166:169], v[206:209], 0
	v_mfma_i32_16x16x64_i8 v[64:67], v[174:177], v[206:209], 0
	v_mfma_i32_16x16x64_i8 v[116:119], v[170:173], v[186:189], v[116:119]
	v_mfma_i32_16x16x64_i8 v[112:115], v[178:181], v[186:189], v[112:115]
	v_mfma_i32_16x16x64_i8 v[100:103], v[170:173], v[194:197], v[100:103]
	v_mfma_i32_16x16x64_i8 v[96:99], v[178:181], v[194:197], v[96:99]
	v_mfma_i32_16x16x64_i8 v[84:87], v[170:173], v[202:205], v[84:87]
	v_mfma_i32_16x16x64_i8 v[80:83], v[178:181], v[202:205], v[80:83]
	v_mfma_i32_16x16x64_i8 v[68:71], v[170:173], v[210:213], v[68:71]
	v_mfma_i32_16x16x64_i8 v[64:67], v[178:181], v[210:213], v[64:67]
	s_setprio 0
	s_barrier
	s_add_i32 s67, s68, s45
	v_lshl_add_u64 v[214:215], s[48:49], 0, v[132:133]
	s_mov_b32 m0, s67
	ds_read_b128 v[182:185], v165 offset:16384
	ds_read_b128 v[186:189], v165 offset:17408
	ds_read_b128 v[190:193], v165 offset:18432
	ds_read_b128 v[194:197], v165 offset:19456
	ds_read_b128 v[198:201], v165 offset:20480
	ds_read_b128 v[202:205], v165 offset:21504
	ds_read_b128 v[206:209], v165 offset:22528
	ds_read_b128 v[210:213], v165 offset:23552
	global_load_lds_dwordx4 v[214:215], off
	s_add_i32 m0, s67, 0x2000
	s_add_u32 s78, s48, 0x80000
	v_lshl_add_u64 v[216:217], s[48:49], 0, v[128:129]
	s_addc_u32 s79, s49, 0
	s_add_i32 s67, s69, s45
	global_load_lds_dwordx4 v[216:217], off
	v_lshl_add_u64 v[218:219], s[78:79], 0, v[132:133]
	s_mov_b32 m0, s67
	v_lshl_add_u64 v[220:221], s[50:51], 0, v[130:131]
	global_load_lds_dwordx4 v[218:219], off
	v_lshl_add_u64 v[218:219], s[78:79], 0, v[128:129]
	s_add_i32 m0, s67, 0x2000
	s_nop 0
	global_load_lds_dwordx4 v[218:219], off
	v_lshl_add_u64 v[218:219], s[50:51], 0, v[134:135]
	s_mov_b32 m0, s54
	s_nop 0
	global_load_lds_dwordx4 v[218:219], off
	s_mov_b32 m0, s55
	s_nop 0
	global_load_lds_dwordx4 v[220:221], off
	s_waitcnt vmcnt(8)
	s_waitcnt lgkmcnt(0)
	s_barrier
	s_setprio 1
	s_waitcnt lgkmcnt(0)
	v_mfma_i32_16x16x64_i8 v[60:63], v[148:151], v[182:185], 0
	v_mfma_i32_16x16x64_i8 v[56:59], v[156:159], v[182:185], 0
	v_mfma_i32_16x16x64_i8 v[44:47], v[148:151], v[190:193], 0
	v_mfma_i32_16x16x64_i8 v[40:43], v[156:159], v[190:193], 0
	v_mfma_i32_16x16x64_i8 v[28:31], v[148:151], v[198:201], 0
	v_mfma_i32_16x16x64_i8 v[24:27], v[156:159], v[198:201], 0
	v_mfma_i32_16x16x64_i8 v[12:15], v[148:151], v[206:209], 0
	v_mfma_i32_16x16x64_i8 v[8:11], v[156:159], v[206:209], 0
	v_mfma_i32_16x16x64_i8 v[60:63], v[152:155], v[186:189], v[60:63]
	v_mfma_i32_16x16x64_i8 v[56:59], v[160:163], v[186:189], v[56:59]
	v_mfma_i32_16x16x64_i8 v[44:47], v[152:155], v[194:197], v[44:47]
	v_mfma_i32_16x16x64_i8 v[40:43], v[160:163], v[194:197], v[40:43]
	v_mfma_i32_16x16x64_i8 v[28:31], v[152:155], v[202:205], v[28:31]
	v_mfma_i32_16x16x64_i8 v[24:27], v[160:163], v[202:205], v[24:27]
	v_mfma_i32_16x16x64_i8 v[12:15], v[152:155], v[210:213], v[12:15]
	v_mfma_i32_16x16x64_i8 v[8:11], v[160:163], v[210:213], v[8:11]
	s_setprio 0
	s_setprio 1
	v_mfma_i32_16x16x64_i8 v[52:55], v[166:169], v[182:185], 0
	v_mfma_i32_16x16x64_i8 v[48:51], v[174:177], v[182:185], 0
	v_mfma_i32_16x16x64_i8 v[36:39], v[166:169], v[190:193], 0
	v_mfma_i32_16x16x64_i8 v[32:35], v[174:177], v[190:193], 0
	v_mfma_i32_16x16x64_i8 v[20:23], v[166:169], v[198:201], 0
	v_mfma_i32_16x16x64_i8 v[16:19], v[174:177], v[198:201], 0
	v_mfma_i32_16x16x64_i8 v[4:7], v[166:169], v[206:209], 0
	v_mfma_i32_16x16x64_i8 v[0:3], v[174:177], v[206:209], 0
	v_mfma_i32_16x16x64_i8 v[52:55], v[170:173], v[186:189], v[52:55]
	v_mfma_i32_16x16x64_i8 v[48:51], v[178:181], v[186:189], v[48:51]
	v_mfma_i32_16x16x64_i8 v[36:39], v[170:173], v[194:197], v[36:39]
	v_mfma_i32_16x16x64_i8 v[32:35], v[178:181], v[194:197], v[32:35]
	v_mfma_i32_16x16x64_i8 v[20:23], v[170:173], v[202:205], v[20:23]
	v_mfma_i32_16x16x64_i8 v[16:19], v[178:181], v[202:205], v[16:19]
	v_mfma_i32_16x16x64_i8 v[4:7], v[170:173], v[210:213], v[4:7]
	v_mfma_i32_16x16x64_i8 v[0:3], v[178:181], v[210:213], v[0:3]
	s_setprio 0
	s_barrier
	s_add_i32 s67, 0, 0x18000
	s_add_i32 s77, 0, 0x1c000
	v_add_u32_e32 v160, s67, v164
	v_add_u32_e32 v178, s77, v164
	ds_read_b128 v[148:151], v160
	ds_read_b128 v[152:155], v160 offset:1024
	ds_read_b128 v[156:159], v160 offset:2048
	ds_read_b128 v[160:163], v160 offset:3072
	ds_read_b128 v[166:169], v178
	ds_read_b128 v[170:173], v178 offset:1024
	ds_read_b128 v[174:177], v178 offset:2048
	ds_read_b128 v[178:181], v178 offset:3072
	s_add_u32 s50, s50, 0x80000
	s_addc_u32 s51, s51, 0
	s_mov_b32 m0, s56
	v_lshl_add_u64 v[222:223], s[50:51], 0, v[134:135]
	ds_read_b128 v[182:185], v165 offset:32768
	ds_read_b128 v[186:189], v165 offset:33792
	ds_read_b128 v[190:193], v165 offset:34816
	ds_read_b128 v[194:197], v165 offset:35840
	ds_read_b128 v[198:201], v165 offset:36864
	ds_read_b128 v[202:205], v165 offset:37888
	ds_read_b128 v[206:209], v165 offset:38912
	ds_read_b128 v[210:213], v165 offset:39936
	global_load_lds_dwordx4 v[222:223], off
	v_lshl_add_u64 v[222:223], s[50:51], 0, v[130:131]
	s_mov_b32 m0, s57
	s_nop 0
	global_load_lds_dwordx4 v[222:223], off
	s_waitcnt vmcnt(8)
	s_waitcnt lgkmcnt(0)
	s_barrier
	s_setprio 1
	s_waitcnt lgkmcnt(0)
	v_mfma_i32_16x16x64_i8 v[124:127], v[148:151], v[182:185], v[124:127]
	v_mfma_i32_16x16x64_i8 v[120:123], v[156:159], v[182:185], v[120:123]
	v_mfma_i32_16x16x64_i8 v[108:111], v[148:151], v[190:193], v[108:111]
	v_mfma_i32_16x16x64_i8 v[104:107], v[156:159], v[190:193], v[104:107]
	v_mfma_i32_16x16x64_i8 v[92:95], v[148:151], v[198:201], v[92:95]
	v_mfma_i32_16x16x64_i8 v[88:91], v[156:159], v[198:201], v[88:91]
	v_mfma_i32_16x16x64_i8 v[76:79], v[148:151], v[206:209], v[76:79]
	v_mfma_i32_16x16x64_i8 v[72:75], v[156:159], v[206:209], v[72:75]
	v_mfma_i32_16x16x64_i8 v[124:127], v[152:155], v[186:189], v[124:127]
	v_mfma_i32_16x16x64_i8 v[120:123], v[160:163], v[186:189], v[120:123]
	v_mfma_i32_16x16x64_i8 v[108:111], v[152:155], v[194:197], v[108:111]
	v_mfma_i32_16x16x64_i8 v[104:107], v[160:163], v[194:197], v[104:107]
	v_mfma_i32_16x16x64_i8 v[92:95], v[152:155], v[202:205], v[92:95]
	v_mfma_i32_16x16x64_i8 v[88:91], v[160:163], v[202:205], v[88:91]
	v_mfma_i32_16x16x64_i8 v[76:79], v[152:155], v[210:213], v[76:79]
	v_mfma_i32_16x16x64_i8 v[72:75], v[160:163], v[210:213], v[72:75]
	s_setprio 0
	s_setprio 1
	v_mfma_i32_16x16x64_i8 v[116:119], v[166:169], v[182:185], v[116:119]
	v_mfma_i32_16x16x64_i8 v[112:115], v[174:177], v[182:185], v[112:115]
	v_mfma_i32_16x16x64_i8 v[100:103], v[166:169], v[190:193], v[100:103]
	v_mfma_i32_16x16x64_i8 v[96:99], v[174:177], v[190:193], v[96:99]
	v_mfma_i32_16x16x64_i8 v[84:87], v[166:169], v[198:201], v[84:87]
	v_mfma_i32_16x16x64_i8 v[80:83], v[174:177], v[198:201], v[80:83]
	v_mfma_i32_16x16x64_i8 v[68:71], v[166:169], v[206:209], v[68:71]
	v_mfma_i32_16x16x64_i8 v[64:67], v[174:177], v[206:209], v[64:67]
	v_mfma_i32_16x16x64_i8 v[116:119], v[170:173], v[186:189], v[116:119]
	v_mfma_i32_16x16x64_i8 v[112:115], v[178:181], v[186:189], v[112:115]
	v_mfma_i32_16x16x64_i8 v[100:103], v[170:173], v[194:197], v[100:103]
	v_mfma_i32_16x16x64_i8 v[96:99], v[178:181], v[194:197], v[96:99]
	v_mfma_i32_16x16x64_i8 v[84:87], v[170:173], v[202:205], v[84:87]
	v_mfma_i32_16x16x64_i8 v[80:83], v[178:181], v[202:205], v[80:83]
	v_mfma_i32_16x16x64_i8 v[68:71], v[170:173], v[210:213], v[68:71]
	v_mfma_i32_16x16x64_i8 v[64:67], v[178:181], v[210:213], v[64:67]
	s_setprio 0
	s_barrier
	s_add_i32 s50, s67, s45
	v_lshl_add_u64 v[214:215], v[214:215], 0, s[18:19]
	s_mov_b32 m0, s50
	ds_read_b128 v[182:185], v165 offset:49152
	ds_read_b128 v[186:189], v165 offset:50176
	ds_read_b128 v[190:193], v165 offset:51200
	ds_read_b128 v[194:197], v165 offset:52224
	ds_read_b128 v[198:201], v165 offset:53248
	ds_read_b128 v[202:205], v165 offset:54272
	ds_read_b128 v[206:209], v165 offset:55296
	ds_read_b128 v[210:213], v165 offset:56320
	global_load_lds_dwordx4 v[214:215], off
	s_add_i32 m0, s50, 0x2000
	s_add_u32 s48, s48, 0x80080
	v_lshl_add_u64 v[214:215], v[216:217], 0, s[18:19]
	s_addc_u32 s49, s49, 0
	s_add_i32 s50, s77, s45
	global_load_lds_dwordx4 v[214:215], off
	v_lshl_add_u64 v[214:215], s[48:49], 0, v[132:133]
	s_mov_b32 m0, s50
	s_nop 0
	global_load_lds_dwordx4 v[214:215], off
	v_lshl_add_u64 v[214:215], s[48:49], 0, v[128:129]
	s_add_i32 m0, s50, 0x2000
	s_nop 0
	global_load_lds_dwordx4 v[214:215], off
	v_lshl_add_u64 v[214:215], v[218:219], 0, s[18:19]
	s_mov_b32 m0, s60
	s_nop 0
	global_load_lds_dwordx4 v[214:215], off
	v_lshl_add_u64 v[214:215], v[220:221], 0, s[18:19]
	s_mov_b32 m0, s61
	s_nop 0
	global_load_lds_dwordx4 v[214:215], off
	s_waitcnt vmcnt(8)
	s_waitcnt lgkmcnt(0)
	s_barrier
	s_setprio 1
	s_waitcnt lgkmcnt(0)
	v_mfma_i32_16x16x64_i8 v[60:63], v[148:151], v[182:185], v[60:63]
	v_mfma_i32_16x16x64_i8 v[56:59], v[156:159], v[182:185], v[56:59]
	v_mfma_i32_16x16x64_i8 v[44:47], v[148:151], v[190:193], v[44:47]
	v_mfma_i32_16x16x64_i8 v[40:43], v[156:159], v[190:193], v[40:43]
	v_mfma_i32_16x16x64_i8 v[28:31], v[148:151], v[198:201], v[28:31]
	v_mfma_i32_16x16x64_i8 v[24:27], v[156:159], v[198:201], v[24:27]
	v_mfma_i32_16x16x64_i8 v[12:15], v[148:151], v[206:209], v[12:15]
	v_mfma_i32_16x16x64_i8 v[8:11], v[156:159], v[206:209], v[8:11]
	v_mfma_i32_16x16x64_i8 v[60:63], v[152:155], v[186:189], v[60:63]
	v_mfma_i32_16x16x64_i8 v[56:59], v[160:163], v[186:189], v[56:59]
	v_mfma_i32_16x16x64_i8 v[44:47], v[152:155], v[194:197], v[44:47]
	v_mfma_i32_16x16x64_i8 v[40:43], v[160:163], v[194:197], v[40:43]
	v_mfma_i32_16x16x64_i8 v[28:31], v[152:155], v[202:205], v[28:31]
	v_mfma_i32_16x16x64_i8 v[24:27], v[160:163], v[202:205], v[24:27]
	v_mfma_i32_16x16x64_i8 v[12:15], v[152:155], v[210:213], v[12:15]
	v_mfma_i32_16x16x64_i8 v[8:11], v[160:163], v[210:213], v[8:11]
	s_setprio 0
	s_setprio 1
	v_mfma_i32_16x16x64_i8 v[52:55], v[166:169], v[182:185], v[52:55]
	v_mfma_i32_16x16x64_i8 v[48:51], v[174:177], v[182:185], v[48:51]
	v_mfma_i32_16x16x64_i8 v[36:39], v[166:169], v[190:193], v[36:39]
	v_mfma_i32_16x16x64_i8 v[32:35], v[174:177], v[190:193], v[32:35]
	v_mfma_i32_16x16x64_i8 v[20:23], v[166:169], v[198:201], v[20:23]
	v_mfma_i32_16x16x64_i8 v[16:19], v[174:177], v[198:201], v[16:19]
	v_mfma_i32_16x16x64_i8 v[4:7], v[166:169], v[206:209], v[4:7]
	v_mfma_i32_16x16x64_i8 v[0:3], v[174:177], v[206:209], v[0:3]
	v_mfma_i32_16x16x64_i8 v[52:55], v[170:173], v[186:189], v[52:55]
	v_mfma_i32_16x16x64_i8 v[48:51], v[178:181], v[186:189], v[48:51]
	v_mfma_i32_16x16x64_i8 v[36:39], v[170:173], v[194:197], v[36:39]
	v_mfma_i32_16x16x64_i8 v[32:35], v[178:181], v[194:197], v[32:35]
	v_mfma_i32_16x16x64_i8 v[20:23], v[170:173], v[202:205], v[20:23]
	v_mfma_i32_16x16x64_i8 v[16:19], v[178:181], v[202:205], v[16:19]
	v_mfma_i32_16x16x64_i8 v[4:7], v[170:173], v[210:213], v[4:7]
	v_mfma_i32_16x16x64_i8 v[0:3], v[178:181], v[210:213], v[0:3]
	s_setprio 0
	s_barrier
	s_add_i32 s76, s76, 2
	s_add_u32 s46, s46, 0x100
	s_addc_u32 s47, s47, 0
	s_cmp_gt_u32 s76, 29
	s_cbranch_scc1 .LBB0_636
	s_branch .LBB0_634

.LBB0_770:
	s_ashr_i32 s47, s46, 31
	s_lshl_b64 s[48:49], s[46:47], 20
	s_add_u32 s48, s16, s48
	s_addc_u32 s49, s17, s49
	s_and_b64 s[50:51], s[6:7], exec
	s_cselect_b32 s47, s49, s55
	s_cselect_b32 s75, s48, s54
	s_ashr_i32 s39, s38, 31
	s_lshl_b64 s[50:51], s[38:39], 20
	s_add_u32 s50, s2, s50
	s_addc_u32 s51, s31, s51
	s_and_b64 s[58:59], s[6:7], exec
	s_cselect_b32 s39, s51, s57
	s_cselect_b32 s76, s50, s56
	s_add_u32 s54, s54, 0x80080
	s_addc_u32 s55, s55, 0
	s_add_u32 s77, s56, 0x100
	s_addc_u32 s78, s57, 0
	s_mov_b32 s79, -2
	ds_read_b128 v[144:147], v153
	ds_read_b128 v[148:151], v153 offset:1024
	ds_read_b128 v[156:159], v153 offset:2048
	ds_read_b128 v[160:163], v153 offset:3072
	ds_read_b128 v[164:167], v154
	ds_read_b128 v[168:171], v154 offset:1024
	ds_read_b128 v[172:175], v154 offset:2048
	ds_read_b128 v[176:179], v154 offset:3072
	s_add_u32 s56, s54, 0xfff80080
	s_addc_u32 s57, s55, -1
	s_cmp_eq_u32 s79, 28
	s_cselect_b32 s59, s47, s57
	s_cselect_b32 s58, s75, s56
	s_cselect_b32 s57, s39, s78
	s_cselect_b32 s56, s76, s77
	v_lshl_add_u64 v[212:213], s[54:55], 0, v[136:137]
	s_add_i32 m0, s37, 0xc000
	ds_read_b128 v[180:183], v155
	ds_read_b128 v[184:187], v155 offset:1024
	ds_read_b128 v[188:191], v155 offset:2048
	ds_read_b128 v[192:195], v155 offset:3072
	ds_read_b128 v[196:199], v155 offset:4096
	ds_read_b128 v[200:203], v155 offset:5120
	ds_read_b128 v[204:207], v155 offset:6144
	ds_read_b128 v[208:211], v155 offset:7168
	global_load_lds_dwordx4 v[212:213], off
	v_lshl_add_u64 v[212:213], s[54:55], 0, v[138:139]
	s_add_i32 m0, s37, 0xe000
	s_nop 0
	global_load_lds_dwordx4 v[212:213], off
	s_waitcnt vmcnt(16)
	s_waitcnt lgkmcnt(0)
	s_barrier
	s_setprio 1
	s_waitcnt lgkmcnt(0)
	v_mfma_i32_16x16x64_i8 v[124:127], v[144:147], v[180:183], 0
	v_mfma_i32_16x16x64_i8 v[120:123], v[156:159], v[180:183], 0
	v_mfma_i32_16x16x64_i8 v[108:111], v[144:147], v[188:191], 0
	v_mfma_i32_16x16x64_i8 v[104:107], v[156:159], v[188:191], 0
	v_mfma_i32_16x16x64_i8 v[92:95], v[144:147], v[196:199], 0
	v_mfma_i32_16x16x64_i8 v[88:91], v[156:159], v[196:199], 0
	v_mfma_i32_16x16x64_i8 v[76:79], v[144:147], v[204:207], 0
	v_mfma_i32_16x16x64_i8 v[72:75], v[156:159], v[204:207], 0
	v_mfma_i32_16x16x64_i8 v[124:127], v[148:151], v[184:187], v[124:127]
	v_mfma_i32_16x16x64_i8 v[120:123], v[160:163], v[184:187], v[120:123]
	v_mfma_i32_16x16x64_i8 v[108:111], v[148:151], v[192:195], v[108:111]
	v_mfma_i32_16x16x64_i8 v[104:107], v[160:163], v[192:195], v[104:107]
	v_mfma_i32_16x16x64_i8 v[92:95], v[148:151], v[200:203], v[92:95]
	v_mfma_i32_16x16x64_i8 v[88:91], v[160:163], v[200:203], v[88:91]
	v_mfma_i32_16x16x64_i8 v[76:79], v[148:151], v[208:211], v[76:79]
	v_mfma_i32_16x16x64_i8 v[72:75], v[160:163], v[208:211], v[72:75]
	s_setprio 0
	s_setprio 1
	v_mfma_i32_16x16x64_i8 v[116:119], v[164:167], v[180:183], 0
	v_mfma_i32_16x16x64_i8 v[112:115], v[172:175], v[180:183], 0
	v_mfma_i32_16x16x64_i8 v[100:103], v[164:167], v[188:191], 0
	v_mfma_i32_16x16x64_i8 v[96:99], v[172:175], v[188:191], 0
	v_mfma_i32_16x16x64_i8 v[84:87], v[164:167], v[196:199], 0
	v_mfma_i32_16x16x64_i8 v[80:83], v[172:175], v[196:199], 0
	v_mfma_i32_16x16x64_i8 v[68:71], v[164:167], v[204:207], 0
	v_mfma_i32_16x16x64_i8 v[64:67], v[172:175], v[204:207], 0
	v_mfma_i32_16x16x64_i8 v[116:119], v[168:171], v[184:187], v[116:119]
	v_mfma_i32_16x16x64_i8 v[112:115], v[176:179], v[184:187], v[112:115]
	v_mfma_i32_16x16x64_i8 v[100:103], v[168:171], v[192:195], v[100:103]
	v_mfma_i32_16x16x64_i8 v[96:99], v[176:179], v[192:195], v[96:99]
	v_mfma_i32_16x16x64_i8 v[84:87], v[168:171], v[200:203], v[84:87]
	v_mfma_i32_16x16x64_i8 v[80:83], v[176:179], v[200:203], v[80:83]
	v_mfma_i32_16x16x64_i8 v[68:71], v[168:171], v[208:211], v[68:71]
	v_mfma_i32_16x16x64_i8 v[64:67], v[176:179], v[208:211], v[64:67]
	s_setprio 0
	s_barrier
	s_add_i32 s80, s72, s34
	v_lshl_add_u64 v[212:213], s[56:57], 0, v[132:133]
	s_mov_b32 m0, s80
	ds_read_b128 v[180:183], v155 offset:16384
	ds_read_b128 v[184:187], v155 offset:17408
	ds_read_b128 v[188:191], v155 offset:18432
	ds_read_b128 v[192:195], v155 offset:19456
	ds_read_b128 v[196:199], v155 offset:20480
	ds_read_b128 v[200:203], v155 offset:21504
	ds_read_b128 v[204:207], v155 offset:22528
	ds_read_b128 v[208:211], v155 offset:23552
	global_load_lds_dwordx4 v[212:213], off
	s_add_i32 m0, s80, 0x2000
	s_add_u32 s80, s56, 0x80000
	v_lshl_add_u64 v[214:215], s[56:57], 0, v[128:129]
	s_addc_u32 s81, s57, 0
	s_add_i32 s82, s73, s34
	global_load_lds_dwordx4 v[214:215], off
	v_lshl_add_u64 v[216:217], s[80:81], 0, v[132:133]
	s_mov_b32 m0, s82
	v_lshl_add_u64 v[218:219], s[58:59], 0, v[130:131]
	global_load_lds_dwordx4 v[216:217], off
	v_lshl_add_u64 v[216:217], s[80:81], 0, v[128:129]
	s_add_i32 m0, s82, 0x2000
	s_nop 0
	global_load_lds_dwordx4 v[216:217], off
	v_lshl_add_u64 v[216:217], s[58:59], 0, v[134:135]
	s_mov_b32 m0, s37
	s_nop 0
	global_load_lds_dwordx4 v[216:217], off
	s_mov_b32 m0, s45
	s_nop 0
	global_load_lds_dwordx4 v[218:219], off
	s_waitcnt vmcnt(8)
	s_waitcnt lgkmcnt(0)
	s_barrier
	s_setprio 1
	s_waitcnt lgkmcnt(0)
	v_mfma_i32_16x16x64_i8 v[60:63], v[144:147], v[180:183], 0
	v_mfma_i32_16x16x64_i8 v[56:59], v[156:159], v[180:183], 0
	v_mfma_i32_16x16x64_i8 v[44:47], v[144:147], v[188:191], 0
	v_mfma_i32_16x16x64_i8 v[40:43], v[156:159], v[188:191], 0
	v_mfma_i32_16x16x64_i8 v[28:31], v[144:147], v[196:199], 0
	v_mfma_i32_16x16x64_i8 v[24:27], v[156:159], v[196:199], 0
	v_mfma_i32_16x16x64_i8 v[12:15], v[144:147], v[204:207], 0
	v_mfma_i32_16x16x64_i8 v[8:11], v[156:159], v[204:207], 0
	v_mfma_i32_16x16x64_i8 v[60:63], v[148:151], v[184:187], v[60:63]
	v_mfma_i32_16x16x64_i8 v[56:59], v[160:163], v[184:187], v[56:59]
	v_mfma_i32_16x16x64_i8 v[44:47], v[148:151], v[192:195], v[44:47]
	v_mfma_i32_16x16x64_i8 v[40:43], v[160:163], v[192:195], v[40:43]
	v_mfma_i32_16x16x64_i8 v[28:31], v[148:151], v[200:203], v[28:31]
	v_mfma_i32_16x16x64_i8 v[24:27], v[160:163], v[200:203], v[24:27]
	v_mfma_i32_16x16x64_i8 v[12:15], v[148:151], v[208:211], v[12:15]
	v_mfma_i32_16x16x64_i8 v[8:11], v[160:163], v[208:211], v[8:11]
	s_setprio 0
	s_setprio 1
	v_mfma_i32_16x16x64_i8 v[52:55], v[164:167], v[180:183], 0
	v_mfma_i32_16x16x64_i8 v[48:51], v[172:175], v[180:183], 0
	v_mfma_i32_16x16x64_i8 v[36:39], v[164:167], v[188:191], 0
	v_mfma_i32_16x16x64_i8 v[32:35], v[172:175], v[188:191], 0
	v_mfma_i32_16x16x64_i8 v[20:23], v[164:167], v[196:199], 0
	v_mfma_i32_16x16x64_i8 v[16:19], v[172:175], v[196:199], 0
	v_mfma_i32_16x16x64_i8 v[4:7], v[164:167], v[204:207], 0
	v_mfma_i32_16x16x64_i8 v[0:3], v[172:175], v[204:207], 0
	v_mfma_i32_16x16x64_i8 v[52:55], v[168:171], v[184:187], v[52:55]
	v_mfma_i32_16x16x64_i8 v[48:51], v[176:179], v[184:187], v[48:51]
	v_mfma_i32_16x16x64_i8 v[36:39], v[168:171], v[192:195], v[36:39]
	v_mfma_i32_16x16x64_i8 v[32:35], v[176:179], v[192:195], v[32:35]
	v_mfma_i32_16x16x64_i8 v[20:23], v[168:171], v[200:203], v[20:23]
	v_mfma_i32_16x16x64_i8 v[16:19], v[176:179], v[200:203], v[16:19]
	v_mfma_i32_16x16x64_i8 v[4:7], v[168:171], v[208:211], v[4:7]
	v_mfma_i32_16x16x64_i8 v[0:3], v[176:179], v[208:211], v[0:3]
	s_setprio 0
	s_barrier
	s_add_i32 s80, 0, 0x18000
	s_add_i32 s81, 0, 0x1c000
	v_add_u32_e32 v160, s80, v152
	v_add_u32_e32 v176, s81, v152
	ds_read_b128 v[144:147], v160
	ds_read_b128 v[148:151], v160 offset:1024
	ds_read_b128 v[156:159], v160 offset:2048
	ds_read_b128 v[160:163], v160 offset:3072
	ds_read_b128 v[164:167], v176
	ds_read_b128 v[168:171], v176 offset:1024
	ds_read_b128 v[172:175], v176 offset:2048
	ds_read_b128 v[176:179], v176 offset:3072
	s_add_u32 s58, s58, 0x80000
	s_addc_u32 s59, s59, 0
	s_mov_b32 m0, s53
	v_lshl_add_u64 v[220:221], s[58:59], 0, v[134:135]
	ds_read_b128 v[180:183], v155 offset:32768
	ds_read_b128 v[184:187], v155 offset:33792
	ds_read_b128 v[188:191], v155 offset:34816
	ds_read_b128 v[192:195], v155 offset:35840
	ds_read_b128 v[196:199], v155 offset:36864
	ds_read_b128 v[200:203], v155 offset:37888
	ds_read_b128 v[204:207], v155 offset:38912
	ds_read_b128 v[208:211], v155 offset:39936
	global_load_lds_dwordx4 v[220:221], off
	v_lshl_add_u64 v[220:221], s[58:59], 0, v[130:131]
	s_mov_b32 m0, s60
	s_nop 0
	global_load_lds_dwordx4 v[220:221], off
	s_waitcnt vmcnt(8)
	s_waitcnt lgkmcnt(0)
	s_barrier
	s_setprio 1
	s_waitcnt lgkmcnt(0)
	v_mfma_i32_16x16x64_i8 v[124:127], v[144:147], v[180:183], v[124:127]
	v_mfma_i32_16x16x64_i8 v[120:123], v[156:159], v[180:183], v[120:123]
	v_mfma_i32_16x16x64_i8 v[108:111], v[144:147], v[188:191], v[108:111]
	v_mfma_i32_16x16x64_i8 v[104:107], v[156:159], v[188:191], v[104:107]
	v_mfma_i32_16x16x64_i8 v[92:95], v[144:147], v[196:199], v[92:95]
	v_mfma_i32_16x16x64_i8 v[88:91], v[156:159], v[196:199], v[88:91]
	v_mfma_i32_16x16x64_i8 v[76:79], v[144:147], v[204:207], v[76:79]
	v_mfma_i32_16x16x64_i8 v[72:75], v[156:159], v[204:207], v[72:75]
	v_mfma_i32_16x16x64_i8 v[124:127], v[148:151], v[184:187], v[124:127]
	v_mfma_i32_16x16x64_i8 v[120:123], v[160:163], v[184:187], v[120:123]
	v_mfma_i32_16x16x64_i8 v[108:111], v[148:151], v[192:195], v[108:111]
	v_mfma_i32_16x16x64_i8 v[104:107], v[160:163], v[192:195], v[104:107]
	v_mfma_i32_16x16x64_i8 v[92:95], v[148:151], v[200:203], v[92:95]
	v_mfma_i32_16x16x64_i8 v[88:91], v[160:163], v[200:203], v[88:91]
	v_mfma_i32_16x16x64_i8 v[76:79], v[148:151], v[208:211], v[76:79]
	v_mfma_i32_16x16x64_i8 v[72:75], v[160:163], v[208:211], v[72:75]
	s_setprio 0
	s_setprio 1
	v_mfma_i32_16x16x64_i8 v[116:119], v[164:167], v[180:183], v[116:119]
	v_mfma_i32_16x16x64_i8 v[112:115], v[172:175], v[180:183], v[112:115]
	v_mfma_i32_16x16x64_i8 v[100:103], v[164:167], v[188:191], v[100:103]
	v_mfma_i32_16x16x64_i8 v[96:99], v[172:175], v[188:191], v[96:99]
	v_mfma_i32_16x16x64_i8 v[84:87], v[164:167], v[196:199], v[84:87]
	v_mfma_i32_16x16x64_i8 v[80:83], v[172:175], v[196:199], v[80:83]
	v_mfma_i32_16x16x64_i8 v[68:71], v[164:167], v[204:207], v[68:71]
	v_mfma_i32_16x16x64_i8 v[64:67], v[172:175], v[204:207], v[64:67]
	v_mfma_i32_16x16x64_i8 v[116:119], v[168:171], v[184:187], v[116:119]
	v_mfma_i32_16x16x64_i8 v[112:115], v[176:179], v[184:187], v[112:115]
	v_mfma_i32_16x16x64_i8 v[100:103], v[168:171], v[192:195], v[100:103]
	v_mfma_i32_16x16x64_i8 v[96:99], v[176:179], v[192:195], v[96:99]
	v_mfma_i32_16x16x64_i8 v[84:87], v[168:171], v[200:203], v[84:87]
	v_mfma_i32_16x16x64_i8 v[80:83], v[176:179], v[200:203], v[80:83]
	v_mfma_i32_16x16x64_i8 v[68:71], v[168:171], v[208:211], v[68:71]
	v_mfma_i32_16x16x64_i8 v[64:67], v[176:179], v[208:211], v[64:67]
	s_setprio 0
	s_barrier
	s_add_i32 s58, s80, s34
	v_lshl_add_u64 v[212:213], v[212:213], 0, s[26:27]
	s_mov_b32 m0, s58
	ds_read_b128 v[180:183], v155 offset:49152
	ds_read_b128 v[184:187], v155 offset:50176
	ds_read_b128 v[188:191], v155 offset:51200
	ds_read_b128 v[192:195], v155 offset:52224
	ds_read_b128 v[196:199], v155 offset:53248
	ds_read_b128 v[200:203], v155 offset:54272
	ds_read_b128 v[204:207], v155 offset:55296
	ds_read_b128 v[208:211], v155 offset:56320
	global_load_lds_dwordx4 v[212:213], off
	s_add_i32 m0, s58, 0x2000
	s_add_u32 s56, s56, 0x80080
	v_lshl_add_u64 v[212:213], v[214:215], 0, s[26:27]
	s_addc_u32 s57, s57, 0
	s_add_i32 s58, s81, s34
	global_load_lds_dwordx4 v[212:213], off
	v_lshl_add_u64 v[212:213], s[56:57], 0, v[132:133]
	s_mov_b32 m0, s58
	s_nop 0
	global_load_lds_dwordx4 v[212:213], off
	v_lshl_add_u64 v[212:213], s[56:57], 0, v[128:129]
	s_add_i32 m0, s58, 0x2000
	s_nop 0
	global_load_lds_dwordx4 v[212:213], off
	v_lshl_add_u64 v[212:213], v[216:217], 0, s[26:27]
	s_mov_b32 m0, s63
	s_nop 0
	global_load_lds_dwordx4 v[212:213], off
	v_lshl_add_u64 v[212:213], v[218:219], 0, s[26:27]
	s_mov_b32 m0, s70
	s_nop 0
	global_load_lds_dwordx4 v[212:213], off
	s_waitcnt vmcnt(8)
	s_waitcnt lgkmcnt(0)
	s_barrier
	s_setprio 1
	s_waitcnt lgkmcnt(0)
	v_mfma_i32_16x16x64_i8 v[60:63], v[144:147], v[180:183], v[60:63]
	v_mfma_i32_16x16x64_i8 v[56:59], v[156:159], v[180:183], v[56:59]
	v_mfma_i32_16x16x64_i8 v[44:47], v[144:147], v[188:191], v[44:47]
	v_mfma_i32_16x16x64_i8 v[40:43], v[156:159], v[188:191], v[40:43]
	v_mfma_i32_16x16x64_i8 v[28:31], v[144:147], v[196:199], v[28:31]
	v_mfma_i32_16x16x64_i8 v[24:27], v[156:159], v[196:199], v[24:27]
	v_mfma_i32_16x16x64_i8 v[12:15], v[144:147], v[204:207], v[12:15]
	v_mfma_i32_16x16x64_i8 v[8:11], v[156:159], v[204:207], v[8:11]
	v_mfma_i32_16x16x64_i8 v[60:63], v[148:151], v[184:187], v[60:63]
	v_mfma_i32_16x16x64_i8 v[56:59], v[160:163], v[184:187], v[56:59]
	v_mfma_i32_16x16x64_i8 v[44:47], v[148:151], v[192:195], v[44:47]
	v_mfma_i32_16x16x64_i8 v[40:43], v[160:163], v[192:195], v[40:43]
	v_mfma_i32_16x16x64_i8 v[28:31], v[148:151], v[200:203], v[28:31]
	v_mfma_i32_16x16x64_i8 v[24:27], v[160:163], v[200:203], v[24:27]
	v_mfma_i32_16x16x64_i8 v[12:15], v[148:151], v[208:211], v[12:15]
	v_mfma_i32_16x16x64_i8 v[8:11], v[160:163], v[208:211], v[8:11]
	s_setprio 0
	s_setprio 1
	v_mfma_i32_16x16x64_i8 v[52:55], v[164:167], v[180:183], v[52:55]
	v_mfma_i32_16x16x64_i8 v[48:51], v[172:175], v[180:183], v[48:51]
	v_mfma_i32_16x16x64_i8 v[36:39], v[164:167], v[188:191], v[36:39]
	v_mfma_i32_16x16x64_i8 v[32:35], v[172:175], v[188:191], v[32:35]
	v_mfma_i32_16x16x64_i8 v[20:23], v[164:167], v[196:199], v[20:23]
	v_mfma_i32_16x16x64_i8 v[16:19], v[172:175], v[196:199], v[16:19]
	v_mfma_i32_16x16x64_i8 v[4:7], v[164:167], v[204:207], v[4:7]
	v_mfma_i32_16x16x64_i8 v[0:3], v[172:175], v[204:207], v[0:3]
	v_mfma_i32_16x16x64_i8 v[52:55], v[168:171], v[184:187], v[52:55]
	v_mfma_i32_16x16x64_i8 v[48:51], v[176:179], v[184:187], v[48:51]
	v_mfma_i32_16x16x64_i8 v[36:39], v[168:171], v[192:195], v[36:39]
	v_mfma_i32_16x16x64_i8 v[32:35], v[176:179], v[192:195], v[32:35]
	v_mfma_i32_16x16x64_i8 v[20:23], v[168:171], v[200:203], v[20:23]
	v_mfma_i32_16x16x64_i8 v[16:19], v[176:179], v[200:203], v[16:19]
	v_mfma_i32_16x16x64_i8 v[4:7], v[168:171], v[208:211], v[4:7]
	v_mfma_i32_16x16x64_i8 v[0:3], v[176:179], v[208:211], v[0:3]
	s_setprio 0
	s_barrier
	s_add_i32 s79, s79, 2
	s_add_u32 s54, s54, 0x100
	s_addc_u32 s55, s55, 0
	s_add_u32 s77, s77, 0x100
	s_addc_u32 s78, s78, 0
	s_cmp_gt_u32 s79, 29
	s_cbranch_scc1 .Lpost_p6

.LBB0_977:
	s_add_u32 s75, s46, 0x100
	s_addc_u32 s76, s47, 0
	s_mov_b32 s77, -2
	ds_read_b128 v[144:147], v153
	ds_read_b128 v[148:151], v153 offset:1024
	ds_read_b128 v[156:159], v153 offset:2048
	ds_read_b128 v[160:163], v153 offset:3072
	ds_read_b128 v[164:167], v154
	ds_read_b128 v[168:171], v154 offset:1024
	ds_read_b128 v[172:175], v154 offset:2048
	ds_read_b128 v[176:179], v154 offset:3072
	s_add_u32 s46, s40, 0x100
	s_addc_u32 s47, s41, 0
	s_cmpk_eq_i32 s77, 0x52
	s_cselect_b32 s51, s9, s47
	s_cselect_b32 s50, s8, s46
	s_cselect_b32 s49, s39, s76
	s_cselect_b32 s48, s38, s75
	v_lshl_add_u64 v[212:213], s[40:41], 0, v[136:137]
	s_add_i32 m0, s52, 0xc000
	ds_read_b128 v[180:183], v155
	ds_read_b128 v[184:187], v155 offset:1024
	ds_read_b128 v[188:191], v155 offset:2048
	ds_read_b128 v[192:195], v155 offset:3072
	ds_read_b128 v[196:199], v155 offset:4096
	ds_read_b128 v[200:203], v155 offset:5120
	ds_read_b128 v[204:207], v155 offset:6144
	ds_read_b128 v[208:211], v155 offset:7168
	global_load_lds_dwordx4 v[212:213], off
	v_lshl_add_u64 v[212:213], s[40:41], 0, v[138:139]
	s_add_i32 m0, s52, 0xe000
	s_nop 0
	global_load_lds_dwordx4 v[212:213], off
	s_waitcnt vmcnt(24)
	s_waitcnt lgkmcnt(0)
	s_barrier
	s_setprio 1
	s_waitcnt lgkmcnt(0)
	v_mfma_i32_16x16x64_i8 v[124:127], v[144:147], v[180:183], 0
	v_mfma_i32_16x16x64_i8 v[120:123], v[156:159], v[180:183], 0
	v_mfma_i32_16x16x64_i8 v[108:111], v[144:147], v[188:191], 0
	v_mfma_i32_16x16x64_i8 v[104:107], v[156:159], v[188:191], 0
	v_mfma_i32_16x16x64_i8 v[92:95], v[144:147], v[196:199], 0
	v_mfma_i32_16x16x64_i8 v[88:91], v[156:159], v[196:199], 0
	v_mfma_i32_16x16x64_i8 v[76:79], v[144:147], v[204:207], 0
	v_mfma_i32_16x16x64_i8 v[72:75], v[156:159], v[204:207], 0
	v_mfma_i32_16x16x64_i8 v[124:127], v[148:151], v[184:187], v[124:127]
	v_mfma_i32_16x16x64_i8 v[120:123], v[160:163], v[184:187], v[120:123]
	v_mfma_i32_16x16x64_i8 v[108:111], v[148:151], v[192:195], v[108:111]
	v_mfma_i32_16x16x64_i8 v[104:107], v[160:163], v[192:195], v[104:107]
	v_mfma_i32_16x16x64_i8 v[92:95], v[148:151], v[200:203], v[92:95]
	v_mfma_i32_16x16x64_i8 v[88:91], v[160:163], v[200:203], v[88:91]
	v_mfma_i32_16x16x64_i8 v[76:79], v[148:151], v[208:211], v[76:79]
	v_mfma_i32_16x16x64_i8 v[72:75], v[160:163], v[208:211], v[72:75]
	s_setprio 0
	s_setprio 1
	v_mfma_i32_16x16x64_i8 v[116:119], v[164:167], v[180:183], 0
	v_mfma_i32_16x16x64_i8 v[112:115], v[172:175], v[180:183], 0
	v_mfma_i32_16x16x64_i8 v[100:103], v[164:167], v[188:191], 0
	v_mfma_i32_16x16x64_i8 v[96:99], v[172:175], v[188:191], 0
	v_mfma_i32_16x16x64_i8 v[84:87], v[164:167], v[196:199], 0
	v_mfma_i32_16x16x64_i8 v[80:83], v[172:175], v[196:199], 0
	v_mfma_i32_16x16x64_i8 v[68:71], v[164:167], v[204:207], 0
	v_mfma_i32_16x16x64_i8 v[64:67], v[172:175], v[204:207], 0
	v_mfma_i32_16x16x64_i8 v[116:119], v[168:171], v[184:187], v[116:119]
	v_mfma_i32_16x16x64_i8 v[112:115], v[176:179], v[184:187], v[112:115]
	v_mfma_i32_16x16x64_i8 v[100:103], v[168:171], v[192:195], v[100:103]
	v_mfma_i32_16x16x64_i8 v[96:99], v[176:179], v[192:195], v[96:99]
	v_mfma_i32_16x16x64_i8 v[84:87], v[168:171], v[200:203], v[84:87]
	v_mfma_i32_16x16x64_i8 v[80:83], v[176:179], v[200:203], v[80:83]
	v_mfma_i32_16x16x64_i8 v[68:71], v[168:171], v[208:211], v[68:71]
	v_mfma_i32_16x16x64_i8 v[64:67], v[176:179], v[208:211], v[64:67]
	s_setprio 0
	s_barrier
	s_add_i32 s40, s61, s35
	v_lshl_add_u64 v[212:213], s[48:49], 0, v[132:133]
	s_mov_b32 m0, s40
	ds_read_b128 v[180:183], v155 offset:16384
	ds_read_b128 v[184:187], v155 offset:17408
	ds_read_b128 v[188:191], v155 offset:18432
	ds_read_b128 v[192:195], v155 offset:19456
	ds_read_b128 v[196:199], v155 offset:20480
	ds_read_b128 v[200:203], v155 offset:21504
	ds_read_b128 v[204:207], v155 offset:22528
	ds_read_b128 v[208:211], v155 offset:23552
	global_load_lds_dwordx4 v[212:213], off
	s_add_i32 m0, s40, 0x2000
	s_add_u32 s40, s48, 0x158000
	v_lshl_add_u64 v[214:215], s[48:49], 0, v[128:129]
	s_addc_u32 s41, s49, 0
	s_add_i32 s78, s62, s35
	global_load_lds_dwordx4 v[214:215], off
	v_lshl_add_u64 v[216:217], s[40:41], 0, v[132:133]
	s_mov_b32 m0, s78
	v_lshl_add_u64 v[218:219], s[50:51], 0, v[130:131]
	global_load_lds_dwordx4 v[216:217], off
	v_lshl_add_u64 v[216:217], s[40:41], 0, v[128:129]
	s_add_i32 m0, s78, 0x2000
	s_nop 0
	global_load_lds_dwordx4 v[216:217], off
	v_lshl_add_u64 v[216:217], s[50:51], 0, v[134:135]
	s_mov_b32 m0, s52
	s_nop 0
	global_load_lds_dwordx4 v[216:217], off
	s_mov_b32 m0, s53
	s_nop 0
	global_load_lds_dwordx4 v[218:219], off
	s_waitcnt vmcnt(8)
	s_waitcnt lgkmcnt(0)
	s_barrier
	s_setprio 1
	s_waitcnt lgkmcnt(0)
	v_mfma_i32_16x16x64_i8 v[60:63], v[144:147], v[180:183], 0
	v_mfma_i32_16x16x64_i8 v[56:59], v[156:159], v[180:183], 0
	v_mfma_i32_16x16x64_i8 v[44:47], v[144:147], v[188:191], 0
	v_mfma_i32_16x16x64_i8 v[40:43], v[156:159], v[188:191], 0
	v_mfma_i32_16x16x64_i8 v[28:31], v[144:147], v[196:199], 0
	v_mfma_i32_16x16x64_i8 v[24:27], v[156:159], v[196:199], 0
	v_mfma_i32_16x16x64_i8 v[12:15], v[144:147], v[204:207], 0
	v_mfma_i32_16x16x64_i8 v[8:11], v[156:159], v[204:207], 0
	v_mfma_i32_16x16x64_i8 v[60:63], v[148:151], v[184:187], v[60:63]
	v_mfma_i32_16x16x64_i8 v[56:59], v[160:163], v[184:187], v[56:59]
	v_mfma_i32_16x16x64_i8 v[44:47], v[148:151], v[192:195], v[44:47]
	v_mfma_i32_16x16x64_i8 v[40:43], v[160:163], v[192:195], v[40:43]
	v_mfma_i32_16x16x64_i8 v[28:31], v[148:151], v[200:203], v[28:31]
	v_mfma_i32_16x16x64_i8 v[24:27], v[160:163], v[200:203], v[24:27]
	v_mfma_i32_16x16x64_i8 v[12:15], v[148:151], v[208:211], v[12:15]
	v_mfma_i32_16x16x64_i8 v[8:11], v[160:163], v[208:211], v[8:11]
	s_setprio 0
	s_setprio 1
	v_mfma_i32_16x16x64_i8 v[52:55], v[164:167], v[180:183], 0
	v_mfma_i32_16x16x64_i8 v[48:51], v[172:175], v[180:183], 0
	v_mfma_i32_16x16x64_i8 v[36:39], v[164:167], v[188:191], 0
	v_mfma_i32_16x16x64_i8 v[32:35], v[172:175], v[188:191], 0
	v_mfma_i32_16x16x64_i8 v[20:23], v[164:167], v[196:199], 0
	v_mfma_i32_16x16x64_i8 v[16:19], v[172:175], v[196:199], 0
	v_mfma_i32_16x16x64_i8 v[4:7], v[164:167], v[204:207], 0
	v_mfma_i32_16x16x64_i8 v[0:3], v[172:175], v[204:207], 0
	v_mfma_i32_16x16x64_i8 v[52:55], v[168:171], v[184:187], v[52:55]
	v_mfma_i32_16x16x64_i8 v[48:51], v[176:179], v[184:187], v[48:51]
	v_mfma_i32_16x16x64_i8 v[36:39], v[168:171], v[192:195], v[36:39]
	v_mfma_i32_16x16x64_i8 v[32:35], v[176:179], v[192:195], v[32:35]
	v_mfma_i32_16x16x64_i8 v[20:23], v[168:171], v[200:203], v[20:23]
	v_mfma_i32_16x16x64_i8 v[16:19], v[176:179], v[200:203], v[16:19]
	v_mfma_i32_16x16x64_i8 v[4:7], v[168:171], v[208:211], v[4:7]
	v_mfma_i32_16x16x64_i8 v[0:3], v[176:179], v[208:211], v[0:3]
	s_setprio 0
	s_barrier
	s_add_i32 s78, 0, 0x18000
	s_add_i32 s79, 0, 0x1c000
	v_add_u32_e32 v160, s78, v152
	v_add_u32_e32 v176, s79, v152
	ds_read_b128 v[144:147], v160
	ds_read_b128 v[148:151], v160 offset:1024
	ds_read_b128 v[156:159], v160 offset:2048
	ds_read_b128 v[160:163], v160 offset:3072
	ds_read_b128 v[164:167], v176
	ds_read_b128 v[168:171], v176 offset:1024
	ds_read_b128 v[172:175], v176 offset:2048
	ds_read_b128 v[176:179], v176 offset:3072
	s_add_u32 s40, s50, 0x158000
	s_addc_u32 s41, s51, 0
	s_mov_b32 m0, s54
	v_lshl_add_u64 v[220:221], s[40:41], 0, v[134:135]
	ds_read_b128 v[180:183], v155 offset:32768
	ds_read_b128 v[184:187], v155 offset:33792
	ds_read_b128 v[188:191], v155 offset:34816
	ds_read_b128 v[192:195], v155 offset:35840
	ds_read_b128 v[196:199], v155 offset:36864
	ds_read_b128 v[200:203], v155 offset:37888
	ds_read_b128 v[204:207], v155 offset:38912
	ds_read_b128 v[208:211], v155 offset:39936
	global_load_lds_dwordx4 v[220:221], off
	v_lshl_add_u64 v[220:221], s[40:41], 0, v[130:131]
	s_mov_b32 m0, s55
	s_nop 0
	global_load_lds_dwordx4 v[220:221], off
	s_waitcnt vmcnt(8)
	s_waitcnt lgkmcnt(0)
	s_barrier
	s_setprio 1
	s_waitcnt lgkmcnt(0)
	v_mfma_i32_16x16x64_i8 v[124:127], v[144:147], v[180:183], v[124:127]
	v_mfma_i32_16x16x64_i8 v[120:123], v[156:159], v[180:183], v[120:123]
	v_mfma_i32_16x16x64_i8 v[108:111], v[144:147], v[188:191], v[108:111]
	v_mfma_i32_16x16x64_i8 v[104:107], v[156:159], v[188:191], v[104:107]
	v_mfma_i32_16x16x64_i8 v[92:95], v[144:147], v[196:199], v[92:95]
	v_mfma_i32_16x16x64_i8 v[88:91], v[156:159], v[196:199], v[88:91]
	v_mfma_i32_16x16x64_i8 v[76:79], v[144:147], v[204:207], v[76:79]
	v_mfma_i32_16x16x64_i8 v[72:75], v[156:159], v[204:207], v[72:75]
	v_mfma_i32_16x16x64_i8 v[124:127], v[148:151], v[184:187], v[124:127]
	v_mfma_i32_16x16x64_i8 v[120:123], v[160:163], v[184:187], v[120:123]
	v_mfma_i32_16x16x64_i8 v[108:111], v[148:151], v[192:195], v[108:111]
	v_mfma_i32_16x16x64_i8 v[104:107], v[160:163], v[192:195], v[104:107]
	v_mfma_i32_16x16x64_i8 v[92:95], v[148:151], v[200:203], v[92:95]
	v_mfma_i32_16x16x64_i8 v[88:91], v[160:163], v[200:203], v[88:91]
	v_mfma_i32_16x16x64_i8 v[76:79], v[148:151], v[208:211], v[76:79]
	v_mfma_i32_16x16x64_i8 v[72:75], v[160:163], v[208:211], v[72:75]
	s_setprio 0
	s_setprio 1
	v_mfma_i32_16x16x64_i8 v[116:119], v[164:167], v[180:183], v[116:119]
	v_mfma_i32_16x16x64_i8 v[112:115], v[172:175], v[180:183], v[112:115]
	v_mfma_i32_16x16x64_i8 v[100:103], v[164:167], v[188:191], v[100:103]
	v_mfma_i32_16x16x64_i8 v[96:99], v[172:175], v[188:191], v[96:99]
	v_mfma_i32_16x16x64_i8 v[84:87], v[164:167], v[196:199], v[84:87]
	v_mfma_i32_16x16x64_i8 v[80:83], v[172:175], v[196:199], v[80:83]
	v_mfma_i32_16x16x64_i8 v[68:71], v[164:167], v[204:207], v[68:71]
	v_mfma_i32_16x16x64_i8 v[64:67], v[172:175], v[204:207], v[64:67]
	v_mfma_i32_16x16x64_i8 v[116:119], v[168:171], v[184:187], v[116:119]
	v_mfma_i32_16x16x64_i8 v[112:115], v[176:179], v[184:187], v[112:115]
	v_mfma_i32_16x16x64_i8 v[100:103], v[168:171], v[192:195], v[100:103]
	v_mfma_i32_16x16x64_i8 v[96:99], v[176:179], v[192:195], v[96:99]
	v_mfma_i32_16x16x64_i8 v[84:87], v[168:171], v[200:203], v[84:87]
	v_mfma_i32_16x16x64_i8 v[80:83], v[176:179], v[200:203], v[80:83]
	v_mfma_i32_16x16x64_i8 v[68:71], v[168:171], v[208:211], v[68:71]
	v_mfma_i32_16x16x64_i8 v[64:67], v[176:179], v[208:211], v[64:67]
	s_setprio 0
	s_barrier
	s_add_i32 s40, s78, s35
	v_lshl_add_u64 v[212:213], v[212:213], 0, s[20:21]
	s_mov_b32 m0, s40
	ds_read_b128 v[180:183], v155 offset:49152
	ds_read_b128 v[184:187], v155 offset:50176
	ds_read_b128 v[188:191], v155 offset:51200
	ds_read_b128 v[192:195], v155 offset:52224
	ds_read_b128 v[196:199], v155 offset:53248
	ds_read_b128 v[200:203], v155 offset:54272
	ds_read_b128 v[204:207], v155 offset:55296
	ds_read_b128 v[208:211], v155 offset:56320
	global_load_lds_dwordx4 v[212:213], off
	s_add_i32 m0, s40, 0x2000
	s_add_u32 s40, s48, 0x158080
	v_lshl_add_u64 v[212:213], v[214:215], 0, s[20:21]
	s_addc_u32 s41, s49, 0
	s_add_i32 s48, s79, s35
	global_load_lds_dwordx4 v[212:213], off
	v_lshl_add_u64 v[212:213], s[40:41], 0, v[132:133]
	s_mov_b32 m0, s48
	s_nop 0
	global_load_lds_dwordx4 v[212:213], off
	v_lshl_add_u64 v[212:213], s[40:41], 0, v[128:129]
	s_add_i32 m0, s48, 0x2000
	s_nop 0
	global_load_lds_dwordx4 v[212:213], off
	v_lshl_add_u64 v[212:213], v[216:217], 0, s[20:21]
	s_mov_b32 m0, s58
	s_nop 0
	global_load_lds_dwordx4 v[212:213], off
	v_lshl_add_u64 v[212:213], v[218:219], 0, s[20:21]
	s_mov_b32 m0, s59
	s_nop 0
	global_load_lds_dwordx4 v[212:213], off
	s_waitcnt vmcnt(8)
	s_waitcnt lgkmcnt(0)
	s_barrier
	s_setprio 1
	s_waitcnt lgkmcnt(0)
	v_mfma_i32_16x16x64_i8 v[60:63], v[144:147], v[180:183], v[60:63]
	v_mfma_i32_16x16x64_i8 v[56:59], v[156:159], v[180:183], v[56:59]
	v_mfma_i32_16x16x64_i8 v[44:47], v[144:147], v[188:191], v[44:47]
	v_mfma_i32_16x16x64_i8 v[40:43], v[156:159], v[188:191], v[40:43]
	v_mfma_i32_16x16x64_i8 v[28:31], v[144:147], v[196:199], v[28:31]
	v_mfma_i32_16x16x64_i8 v[24:27], v[156:159], v[196:199], v[24:27]
	v_mfma_i32_16x16x64_i8 v[12:15], v[144:147], v[204:207], v[12:15]
	v_mfma_i32_16x16x64_i8 v[8:11], v[156:159], v[204:207], v[8:11]
	v_mfma_i32_16x16x64_i8 v[60:63], v[148:151], v[184:187], v[60:63]
	v_mfma_i32_16x16x64_i8 v[56:59], v[160:163], v[184:187], v[56:59]
	v_mfma_i32_16x16x64_i8 v[44:47], v[148:151], v[192:195], v[44:47]
	v_mfma_i32_16x16x64_i8 v[40:43], v[160:163], v[192:195], v[40:43]
	v_mfma_i32_16x16x64_i8 v[28:31], v[148:151], v[200:203], v[28:31]
	v_mfma_i32_16x16x64_i8 v[24:27], v[160:163], v[200:203], v[24:27]
	v_mfma_i32_16x16x64_i8 v[12:15], v[148:151], v[208:211], v[12:15]
	v_mfma_i32_16x16x64_i8 v[8:11], v[160:163], v[208:211], v[8:11]
	s_setprio 0
	s_setprio 1
	v_mfma_i32_16x16x64_i8 v[52:55], v[164:167], v[180:183], v[52:55]
	v_mfma_i32_16x16x64_i8 v[48:51], v[172:175], v[180:183], v[48:51]
	v_mfma_i32_16x16x64_i8 v[36:39], v[164:167], v[188:191], v[36:39]
	v_mfma_i32_16x16x64_i8 v[32:35], v[172:175], v[188:191], v[32:35]
	v_mfma_i32_16x16x64_i8 v[20:23], v[164:167], v[196:199], v[20:23]
	v_mfma_i32_16x16x64_i8 v[16:19], v[172:175], v[196:199], v[16:19]
	v_mfma_i32_16x16x64_i8 v[4:7], v[164:167], v[204:207], v[4:7]
	v_mfma_i32_16x16x64_i8 v[0:3], v[172:175], v[204:207], v[0:3]
	v_mfma_i32_16x16x64_i8 v[52:55], v[168:171], v[184:187], v[52:55]
	v_mfma_i32_16x16x64_i8 v[48:51], v[176:179], v[184:187], v[48:51]
	v_mfma_i32_16x16x64_i8 v[36:39], v[168:171], v[192:195], v[36:39]
	v_mfma_i32_16x16x64_i8 v[32:35], v[176:179], v[192:195], v[32:35]
	v_mfma_i32_16x16x64_i8 v[20:23], v[168:171], v[200:203], v[20:23]
	v_mfma_i32_16x16x64_i8 v[16:19], v[176:179], v[200:203], v[16:19]
	v_mfma_i32_16x16x64_i8 v[4:7], v[168:171], v[208:211], v[4:7]
	v_mfma_i32_16x16x64_i8 v[0:3], v[176:179], v[208:211], v[0:3]
	s_setprio 0
	s_barrier
	s_add_i32 s77, s77, 2
	s_add_u32 s75, s75, 0x100
	s_addc_u32 s76, s76, 0
	s_cmpk_gt_u32 s77, 0x53
	s_mov_b64 s[40:41], s[46:47]
	s_cbranch_scc1 .Lpost_p7
